# out-proj->up and up->down seams: barrier among the 4 workgroups that own the same token tile (same XCD under round-robin placement) instead of the grid barrier; no L2 writeback at these seams
# speedup vs baseline: 1.0046x; 1.0046x over previous
_Z9hymba_fwd4Args:
	s_mov_b32 s101, 0
	s_mov_b32 s100, 0
	v_and_b32_e32 v18, 0x3ff, v0
	s_mov_b64 s[84:85], s[0:1]
	v_cmp_eq_u32_e32 vcc, 0, v18
	s_and_saveexec_b64 s[4:5], vcc
	v_mov_b32_e32 v2, 0
	v_mov_b32_e32 v3, v2
	v_mov_b32_e32 v4, v2
	v_mov_b32_e32 v5, v2
	ds_write_b128 v2, v[2:5] offset:256
	s_or_b64 exec, exec, s[4:5]
	v_cmp_gt_u32_e32 vcc, 4, v18
	s_and_saveexec_b64 s[4:5], vcc
	v_lshlrev_b32_e32 v1, 2, v18
	v_mov_b32_e32 v2, 0
	ds_write_b32 v1, v2 offset:272
	s_or_b64 exec, exec, s[4:5]
	v_and_b32_e32 v1, 63, v18
	v_cmp_eq_u32_e32 vcc, 0, v1
	s_waitcnt lgkmcnt(0)
	s_barrier
	s_and_saveexec_b64 s[4:5], vcc
	s_cbranch_execz .LBB0_8
	s_mov_b64 s[8:9], exec
	v_mbcnt_lo_u32_b32 v1, s8, 0
	v_mbcnt_hi_u32_b32 v1, s9, v1
	s_getreg_b32 s0, hwreg(HW_REG_HW_ID, 0, 7)
	v_cmp_eq_u32_e32 vcc, 0, v1
	s_and_saveexec_b64 s[6:7], vcc
	s_cbranch_execz .LBB0_7
	s_lshr_b32 s0, s0, 2
	s_and_b32 s0, s0, 12
	s_bcnt1_i32_b64 s1, s[8:9]
	v_mov_b32_e32 v2, s0
	v_mov_b32_e32 v3, s1
	ds_add_rtn_u32 v2, v2, v3 offset:272

.LBB0_588:
	s_mov_b64 s[10:11], s[84:85]
	v_mov_b32_e32 v0, v173
	s_getreg_b32 s1, hwreg(HW_REG_XCC_ID, 0, 4)
	s_waitcnt vmcnt(0)
	s_waitcnt lgkmcnt(0)
	s_barrier
	s_getreg_b32 s6, hwreg(HW_REG_HW_ID, 0, 7)
	s_and_b32 s6, s6, 63
	s_lshl_b32 s6, s6, 2
	v_mov_b32_e32 v1, s6
	ds_read_b32 v1, v1
	v_sub_u32_e32 v0, 0, v0
	s_waitcnt lgkmcnt(0)
	v_readfirstlane_b32 s6, v1
	s_lshl_b32 s6, s6, 6
	s_and_b32 s6, s6, 0x3fc0
	v_cmp_eq_u32_e32 vcc, s6, v0
	s_and_saveexec_b64 s[8:9], vcc
	s_cbranch_execz .LBB0_640
	s_load_dwordx2 s[10:11], s[10:11], 0xe0
	s_and_b32 s12, s2, 7
	s_lshl_b32 s12, s12, 3
	s_bfe_u32 s13, s2, 0x30003
	s_add_u32 s12, s12, s13
	s_lshl_b32 s12, s12, 2
	s_add_u32 s12, s12, 0xf500020
	s_add_u32 s101, s101, 4
	v_mov_b32_e32 v1, 1
	s_waitcnt vmcnt(0) lgkmcnt(0)
	s_add_u32 s10, s10, s12
	s_addc_u32 s11, s11, 0
	global_atomic_add v161, v1, s[10:11]
.Lgb_spin_a:
	s_sleep 1
	global_load_dword v1, v161, s[10:11] sc1
	s_waitcnt vmcnt(0)
	v_readfirstlane_b32 s12, v1
	s_cmp_lt_u32 s12, s101
	s_cbranch_scc1 .Lgb_spin_a
	buffer_inv sc1
	s_waitcnt vmcnt(0)

.LBB0_660:
	s_mov_b64 s[10:11], s[84:85]
	v_mov_b32_e32 v0, v173
	s_getreg_b32 s1, hwreg(HW_REG_XCC_ID, 0, 4)
	s_waitcnt vmcnt(0)
	s_barrier
	s_getreg_b32 s6, hwreg(HW_REG_HW_ID, 0, 7)
	s_and_b32 s6, s6, 63
	s_lshl_b32 s6, s6, 2
	v_mov_b32_e32 v1, s6
	ds_read_b32 v1, v1
	v_sub_u32_e32 v0, 0, v0
	s_waitcnt lgkmcnt(0)
	v_readfirstlane_b32 s6, v1
	s_lshl_b32 s6, s6, 6
	s_and_b32 s6, s6, 0x3fc0
	v_cmp_eq_u32_e32 vcc, s6, v0
	s_and_saveexec_b64 s[8:9], vcc
	s_cbranch_execz .LBB0_712
	s_load_dwordx2 s[10:11], s[10:11], 0xe0
	s_and_b32 s12, s2, 7
	s_lshl_b32 s12, s12, 3
	s_bfe_u32 s13, s2, 0x30003
	s_add_u32 s12, s12, s13
	s_lshl_b32 s12, s12, 2
	s_add_u32 s12, s12, 0xf500020
	s_add_u32 s101, s101, 4
	v_mov_b32_e32 v1, 1
	s_waitcnt vmcnt(0) lgkmcnt(0)
	s_add_u32 s10, s10, s12
	s_addc_u32 s11, s11, 0
	global_atomic_add v161, v1, s[10:11]
